# code placement only: 140-byte pad at entry (same loop-head addresses mod 256 as the conversion-loop variant), no other change
# speedup vs baseline: 1.0030x; 1.0030x over previous
; #define LAS __attribute__((address_space(3)))
; __device__ __forceinline__ ParamsPtr params_ptr() { ParamsPtr q = (ParamsPtr)__builtin_amdgcn_kernarg_segment_ptr(); asm volatile("" : "+s"(q)); return q; }
; __device__ __forceinline__ unsigned xb_add(unsigned* p, unsigned v) { return __hip_atomic_fetch_add(p, v, __ATOMIC_RELAXED, __HIP_MEMORY_SCOPE_AGENT); }
; __device__ __forceinline__ unsigned xb_xcc_id() { return (unsigned)__builtin_amdgcn_s_getreg((3 << 11) | 20) & 0xFu; }
; __device__ __forceinline__ XcdBarrier xcd_barrier_post(unsigned* bar, volatile LAS unsigned* st) {
;     XcdBarrier b; b.bar = bar; b.x = xb_xcc_id(); b.st = st;
;     if (threadIdx.x == 0) (void)xb_add(&bar[XB_XCNT(b.x)], 1u);
;     return b;
; __global__ void __launch_bounds__(NTHREADS, 2) fwd_megakernel(Params p_unused) {
;     ...
;     const int lo = params_ptr()->ph_lo, hi = params_ptr()->ph_hi;
;     const int G = gridDim.x, bx = blockIdx.x;
;     int ph = 0;
;     volatile LAS unsigned* xbst = (volatile LAS unsigned*)(ldsl + XB_LDS_OFF);
;     if (threadIdx.x < 4) xbst[threadIdx.x] = 0u;
;     __syncthreads();
;     XcdBarrier xbar; xbar.bar = (unsigned*)(params_ptr()->ws + WS_BAR); xbar.x = 0; xbar.st = xbst;
;     if (hi - lo > 1) xbar = xcd_barrier_post((unsigned*)(params_ptr()->ws + WS_BAR), xbst);
_Z14fwd_megakernel6Params:
	s_nop 0
	s_nop 0
	s_nop 0
	s_nop 0
	s_nop 0
	s_nop 0
	s_nop 0
	s_nop 0
	s_nop 0
	s_nop 0
	s_nop 0
	s_nop 0
	s_nop 0
	s_nop 0
	s_nop 0
	s_nop 0
	s_nop 0
	s_nop 0
	s_nop 0
	s_nop 0
	s_nop 0
	s_nop 0
	s_nop 0
	s_nop 0
	s_nop 0
	s_nop 0
	s_nop 0
	s_nop 0
	s_nop 0
	s_nop 0
	s_nop 0
	s_nop 0
	s_nop 0
	s_nop 0
	s_nop 0
	s_mov_b32 s67, s2
	s_mov_b64 s[70:71], s[0:1]
	s_load_dwordx2 s[68:69], s[0:1], 0xb0
	s_load_dword s2, s[0:1], 0xb8
	s_load_dword s72, s[0:1], 0xa8
	s_mov_b64 s[0:1], s[70:71]
	s_load_dword s73, s[0:1], 0xac
	s_add_u32 s0, s70, 0xb0
	s_addc_u32 s1, s71, 0
	v_and_b32_e32 v232, 0x3ff, v0
	v_writelane_b32 v253, s0, 0
	v_cmp_gt_u32_e32 vcc, 4, v232
	s_nop 0
	v_writelane_b32 v253, s1, 1
	s_and_saveexec_b64 s[0:1], vcc
	v_lshl_add_u32 v1, v232, 2, 0
	v_add_u32_e32 v1, 0x27fc0, v1
	v_mov_b32_e32 v2, 0
	ds_write_b32 v1, v2
	s_or_b64 exec, exec, s[0:1]
	s_mov_b64 s[0:1], s[70:71]
	s_waitcnt lgkmcnt(0)
	s_barrier
	s_load_dwordx2 s[0:1], s[0:1], 0xa0
	s_mov_b32 s3, 0
	v_cmp_eq_u32_e32 vcc, 0, v232
	s_waitcnt lgkmcnt(0)
	s_add_u32 s12, s0, 0x23680000
	s_addc_u32 s13, s1, 0
	s_sub_i32 s28, s73, s72
	s_cmp_lt_i32 s28, 2
	s_cbranch_scc1 .LBB0_7
	s_mov_b64 s[0:1], s[70:71]
	s_load_dwordx2 s[0:1], s[0:1], 0xa0
	s_getreg_b32 s3, hwreg(HW_REG_XCC_ID, 0, 4)
	s_waitcnt lgkmcnt(0)
	s_add_u32 s12, s0, 0x23680000
	s_addc_u32 s13, s1, 0
	s_and_b32 s3, s3, 15
	s_and_saveexec_b64 s[0:1], vcc
	s_cbranch_execz .LBB0_6
	s_mov_b64 s[4:5], exec
	v_mbcnt_lo_u32_b32 v1, s4, 0
	v_mbcnt_hi_u32_b32 v1, s5, v1
	v_cmp_eq_u32_e32 vcc, 0, v1
	s_and_b64 s[6:7], exec, vcc
	s_mov_b64 exec, s[6:7]
	s_cbranch_execz .LBB0_6
	s_lshl_b32 s6, s3, 8
	s_bcnt1_i32_b64 s4, s[4:5]
	v_mov_b32_e32 v1, s6
	v_mov_b32_e32 v2, s4
	global_atomic_add v1, v2, s[12:13] offset:1024
